# accumulator clearing before each GEMM unit with 64-bit zero moves (half the VALU instructions)
# speedup vs baseline: 1.0067x; 1.0067x over previous
.LBB0_52:
	v_lshrrev_b32_e32 v18, 1, v10
	v_and_b32_e32 v18, 24, v18
	s_add_u32 s86, s8, 0x3a900000
	v_and_b32_e32 v17, 15, v10
	v_lshlrev_b32_e32 v19, 1, v18
	v_lshlrev_b32_e32 v10, 2, v10
	s_addc_u32 s91, s9, 0
	v_lshl_or_b32 v144, s21, 6, v17
	v_lshl_or_b32 v17, v17, 6, v19
	s_lshl_b32 s21, s21, 13
	v_and_b32_e32 v10, 32, v10
	v_bitop3_b32 v19, v17, s21, v10 bitop3:0xde
	s_lshl_b32 s21, s24, 5
	s_and_b32 s21, s21, 0x60
	s_add_i32 m0, s35, 0x18000
	v_lshl_add_u64 v[6:7], v[6:7], 0, s[80:81]
	s_lshl_b32 s24, s21, 7
	s_waitcnt vmcnt(2)
	s_barrier
	global_load_lds_dwordx4 v[6:7], off
	v_lshl_add_u64 v[4:5], v[4:5], 0, s[80:81]
	s_add_i32 m0, s35, 0x1a000
	s_add_i32 s95, s35, 0x8000
	s_add_i32 s58, s35, 0xa000
	v_bitop3_b32 v145, v17, s24, v10 bitop3:0xde
	global_load_lds_dwordx4 v[4:5], off
	v_lshl_add_u64 v[2:3], v[2:3], 0, s[80:81]
	s_mov_b32 m0, s95
	s_add_u32 s24, s56, 0x100080
	global_load_lds_dwordx4 v[2:3], off
	v_lshl_add_u64 v[2:3], v[8:9], 0, s[80:81]
	s_mov_b32 m0, s58
	s_addc_u32 s25, s57, 0
	global_load_lds_dwordx4 v[2:3], off
	s_add_i32 m0, s35, 0x1c000
	v_lshl_add_u64 v[2:3], s[24:25], 0, v[0:1]
	global_load_lds_dwordx4 v[2:3], off
	v_lshl_add_u64 v[2:3], s[24:25], 0, v[134:135]
	s_add_i32 m0, s35, 0x1e000
	s_mov_b64 s[12:13], 0x100080
	global_load_lds_dwordx4 v[2:3], off
	v_lshlrev_b32_e32 v2, 16, v11
	v_and_b32_e32 v2, 0xfffe0000, v2
	v_lshl_add_u32 v2, v12, 13, v2
	v_and_b32_e32 v3, 1, v11
	v_lshl_or_b32 v2, v3, 6, v2
	v_lshl_add_u32 v2, v13, 1, v2
	v_mov_b32_e32 v3, v1
	v_lshl_add_u64 v[136:137], v[2:3], 0, s[12:13]
	v_lshlrev_b32_e32 v2, 16, v14
	v_and_b32_e32 v2, 0xfffe0000, v2
	v_lshl_add_u32 v2, v15, 13, v2
	v_and_b32_e32 v3, 1, v14
	v_lshl_or_b32 v2, v3, 6, v2
	s_waitcnt vmcnt(6)
	v_lshl_add_u32 v2, v16, 1, v2
	v_mov_b32_e32 v3, v1
	s_cmpk_lt_u32 s20, 0x100
	v_lshl_add_u64 v[138:139], v[2:3], 0, s[12:13]
	v_mov_b32_e32 v2, 0
	s_cselect_b64 s[60:61], -1, 0
	v_or_b32_e32 v150, s21, v18
	s_mov_b32 s59, 0
	v_add_u32_e32 v151, 0, v19
	v_mov_b64_e32 v[2:3], 0
	v_mov_b64_e32 v[4:5], 0
	v_mov_b64_e32 v[6:7], 0
	v_mov_b64_e32 v[8:9], 0
	v_mov_b64_e32 v[10:11], 0
	v_mov_b64_e32 v[12:13], 0
	v_mov_b64_e32 v[14:15], 0
	v_mov_b64_e32 v[16:17], 0
	v_mov_b64_e32 v[18:19], 0
	v_mov_b64_e32 v[20:21], 0
	v_mov_b64_e32 v[22:23], 0
	v_mov_b64_e32 v[24:25], 0
	v_mov_b64_e32 v[26:27], 0
	v_mov_b64_e32 v[28:29], 0
	v_mov_b64_e32 v[30:31], 0
	v_mov_b64_e32 v[32:33], 0
	v_mov_b64_e32 v[34:35], 0
	v_mov_b64_e32 v[36:37], 0
	v_mov_b64_e32 v[38:39], 0
	v_mov_b64_e32 v[40:41], 0
	v_mov_b64_e32 v[42:43], 0
	v_mov_b64_e32 v[44:45], 0
	v_mov_b64_e32 v[46:47], 0
	v_mov_b64_e32 v[48:49], 0
	v_mov_b64_e32 v[50:51], 0
	v_mov_b64_e32 v[52:53], 0
	v_mov_b64_e32 v[54:55], 0
	v_mov_b64_e32 v[56:57], 0
	v_mov_b64_e32 v[58:59], 0
	v_mov_b64_e32 v[60:61], 0
	v_mov_b64_e32 v[62:63], 0
	v_mov_b64_e32 v[64:65], 0
	v_mov_b64_e32 v[66:67], 0
	v_mov_b64_e32 v[68:69], 0
	v_mov_b64_e32 v[70:71], 0
	v_mov_b64_e32 v[72:73], 0
	v_mov_b64_e32 v[74:75], 0
	v_mov_b64_e32 v[76:77], 0
	v_mov_b64_e32 v[78:79], 0
	v_mov_b64_e32 v[80:81], 0
	v_mov_b64_e32 v[82:83], 0
	v_mov_b64_e32 v[84:85], 0
	v_mov_b64_e32 v[86:87], 0
	v_mov_b64_e32 v[88:89], 0
	v_mov_b64_e32 v[90:91], 0
	v_mov_b64_e32 v[92:93], 0
	v_mov_b64_e32 v[94:95], 0
	v_mov_b64_e32 v[96:97], 0
	v_mov_b64_e32 v[98:99], 0
	v_mov_b64_e32 v[100:101], 0
	v_mov_b64_e32 v[102:103], 0
	v_mov_b64_e32 v[104:105], 0
	v_mov_b64_e32 v[106:107], 0
	v_mov_b64_e32 v[108:109], 0
	v_mov_b64_e32 v[110:111], 0
	v_mov_b64_e32 v[112:113], 0
	v_mov_b64_e32 v[114:115], 0
	v_mov_b64_e32 v[116:117], 0
	v_mov_b64_e32 v[118:119], 0
	v_mov_b64_e32 v[120:121], 0
	v_mov_b64_e32 v[122:123], 0
	v_mov_b64_e32 v[124:125], 0
	v_mov_b64_e32 v[126:127], 0
	v_mov_b64_e32 v[128:129], 0
	s_barrier
	s_branch .LBB0_55
.LBB0_53:
	v_mov_b32_e32 v2, 0
	s_mov_b32 s14, s21
	s_mov_b32 s15, s20
	s_mov_b32 s50, s66
	s_mov_b32 s52, s64
	s_mov_b32 s48, s62
	s_mov_b64 s[56:57], s[72:73]
	s_mov_b64 s[54:55], s[70:71]
	s_mov_b32 s59, s88
	v_mov_b64_e32 v[2:3], 0
	v_mov_b64_e32 v[4:5], 0
	v_mov_b64_e32 v[6:7], 0
	v_mov_b64_e32 v[8:9], 0
	v_mov_b64_e32 v[10:11], 0
	v_mov_b64_e32 v[12:13], 0
	v_mov_b64_e32 v[14:15], 0
	v_mov_b64_e32 v[16:17], 0
	v_mov_b64_e32 v[18:19], 0
	v_mov_b64_e32 v[20:21], 0
	v_mov_b64_e32 v[22:23], 0
	v_mov_b64_e32 v[24:25], 0
	v_mov_b64_e32 v[26:27], 0
	v_mov_b64_e32 v[28:29], 0
	v_mov_b64_e32 v[30:31], 0
	v_mov_b64_e32 v[32:33], 0
	v_mov_b64_e32 v[34:35], 0
	v_mov_b64_e32 v[36:37], 0
	v_mov_b64_e32 v[38:39], 0
	v_mov_b64_e32 v[40:41], 0
	v_mov_b64_e32 v[42:43], 0
	v_mov_b64_e32 v[44:45], 0
	v_mov_b64_e32 v[46:47], 0
	v_mov_b64_e32 v[48:49], 0
	v_mov_b64_e32 v[50:51], 0
	v_mov_b64_e32 v[52:53], 0
	v_mov_b64_e32 v[54:55], 0
	v_mov_b64_e32 v[56:57], 0
	v_mov_b64_e32 v[58:59], 0
	v_mov_b64_e32 v[60:61], 0
	v_mov_b64_e32 v[62:63], 0
	v_mov_b64_e32 v[64:65], 0
	v_mov_b64_e32 v[66:67], 0
	v_mov_b64_e32 v[68:69], 0
	v_mov_b64_e32 v[70:71], 0
	v_mov_b64_e32 v[72:73], 0
	v_mov_b64_e32 v[74:75], 0
	v_mov_b64_e32 v[76:77], 0
	v_mov_b64_e32 v[78:79], 0
	v_mov_b64_e32 v[80:81], 0
	v_mov_b64_e32 v[82:83], 0
	v_mov_b64_e32 v[84:85], 0
	v_mov_b64_e32 v[86:87], 0
	v_mov_b64_e32 v[88:89], 0
	v_mov_b64_e32 v[90:91], 0
	v_mov_b64_e32 v[92:93], 0
	v_mov_b64_e32 v[94:95], 0
	v_mov_b64_e32 v[96:97], 0
	v_mov_b64_e32 v[98:99], 0
	v_mov_b64_e32 v[100:101], 0
	v_mov_b64_e32 v[102:103], 0
	v_mov_b64_e32 v[104:105], 0
	v_mov_b64_e32 v[106:107], 0
	v_mov_b64_e32 v[108:109], 0
	v_mov_b64_e32 v[110:111], 0
	v_mov_b64_e32 v[112:113], 0
	v_mov_b64_e32 v[114:115], 0
	v_mov_b64_e32 v[116:117], 0
	v_mov_b64_e32 v[118:119], 0
	v_mov_b64_e32 v[120:121], 0
	v_mov_b64_e32 v[122:123], 0
	v_mov_b64_e32 v[124:125], 0
	v_mov_b64_e32 v[126:127], 0
	v_mov_b64_e32 v[128:129], 0

.LBB0_100:
	s_lshl_b32 s20, s27, 2
	s_add_u32 s12, s8, s20
	v_lshrrev_b32_e32 v18, 1, v10
	s_addc_u32 s13, s9, 0
	v_and_b32_e32 v18, 24, v18
	s_add_u32 s20, s8, 0x3cc00000
	v_and_b32_e32 v17, 15, v10
	v_lshlrev_b32_e32 v19, 1, v18
	v_lshlrev_b32_e32 v10, 2, v10
	s_addc_u32 s21, s9, 0
	v_lshl_or_b32 v144, s14, 6, v17
	v_lshl_or_b32 v17, v17, 6, v19
	s_lshl_b32 s14, s14, 13
	v_and_b32_e32 v10, 32, v10
	v_bitop3_b32 v19, v17, s14, v10 bitop3:0xde
	s_lshl_b32 s14, s15, 5
	v_writelane_b32 v255, s27, 9
	s_and_b32 s27, s14, 0x60
	s_lshl_b32 s14, s27, 7
	s_add_i32 m0, s45, 0x18000
	v_lshl_add_u64 v[6:7], v[6:7], 0, s[80:81]
	v_bitop3_b32 v145, v17, s14, v10 bitop3:0xde
	s_waitcnt vmcnt(2)
	s_barrier
	global_load_lds_dwordx4 v[6:7], off
	v_lshl_add_u64 v[4:5], v[4:5], 0, s[80:81]
	s_add_i32 m0, s45, 0x1a000
	s_add_i32 s14, s45, 0x8000
	s_add_i32 s15, s45, 0xa000
	global_load_lds_dwordx4 v[4:5], off
	v_lshl_add_u64 v[2:3], v[2:3], 0, s[80:81]
	s_mov_b32 m0, s14
	s_add_u32 s24, s54, 0x40080
	global_load_lds_dwordx4 v[2:3], off
	v_lshl_add_u64 v[2:3], v[8:9], 0, s[80:81]
	s_mov_b32 m0, s15
	s_addc_u32 s25, s55, 0
	global_load_lds_dwordx4 v[2:3], off
	s_add_i32 m0, s45, 0x1c000
	v_lshl_add_u64 v[2:3], s[24:25], 0, v[0:1]
	global_load_lds_dwordx4 v[2:3], off
	v_lshl_add_u64 v[2:3], s[24:25], 0, v[134:135]
	s_add_i32 m0, s45, 0x1e000
	v_writelane_b32 v255, s12, 5
	global_load_lds_dwordx4 v[2:3], off
	v_lshlrev_b32_e32 v2, 14, v11
	v_and_b32_e32 v2, 0xffff8000, v2
	v_lshl_add_u32 v2, v12, 11, v2
	v_and_b32_e32 v3, 1, v11
	v_lshl_or_b32 v2, v3, 6, v2
	v_writelane_b32 v255, s13, 6
	v_lshl_add_u32 v2, v13, 1, v2
	v_mov_b32_e32 v3, v1
	s_mov_b64 s[12:13], 0x40080
	v_lshl_add_u64 v[136:137], v[2:3], 0, s[12:13]
	v_lshlrev_b32_e32 v2, 14, v14
	v_and_b32_e32 v2, 0xffff8000, v2
	v_lshl_add_u32 v2, v15, 11, v2
	v_and_b32_e32 v3, 1, v14
	v_lshl_or_b32 v2, v3, 6, v2
	s_waitcnt vmcnt(6)
	v_lshl_add_u32 v2, v16, 1, v2
	v_mov_b32_e32 v3, v1
	s_cmpk_lt_u32 s26, 0x100
	v_lshl_add_u64 v[138:139], v[2:3], 0, s[12:13]
	v_mov_b32_e32 v2, 0
	s_cselect_b64 s[60:61], -1, 0
	v_or_b32_e32 v150, s27, v18
	s_mov_b32 s88, 0
	v_add_u32_e32 v151, 0, v19
	v_mov_b64_e32 v[2:3], 0
	v_mov_b64_e32 v[4:5], 0
	v_mov_b64_e32 v[6:7], 0
	v_mov_b64_e32 v[8:9], 0
	v_mov_b64_e32 v[10:11], 0
	v_mov_b64_e32 v[12:13], 0
	v_mov_b64_e32 v[14:15], 0
	v_mov_b64_e32 v[16:17], 0
	v_mov_b64_e32 v[18:19], 0
	v_mov_b64_e32 v[20:21], 0
	v_mov_b64_e32 v[22:23], 0
	v_mov_b64_e32 v[24:25], 0
	v_mov_b64_e32 v[26:27], 0
	v_mov_b64_e32 v[28:29], 0
	v_mov_b64_e32 v[30:31], 0
	v_mov_b64_e32 v[32:33], 0
	v_mov_b64_e32 v[34:35], 0
	v_mov_b64_e32 v[36:37], 0
	v_mov_b64_e32 v[38:39], 0
	v_mov_b64_e32 v[40:41], 0
	v_mov_b64_e32 v[42:43], 0
	v_mov_b64_e32 v[44:45], 0
	v_mov_b64_e32 v[46:47], 0
	v_mov_b64_e32 v[48:49], 0
	v_mov_b64_e32 v[50:51], 0
	v_mov_b64_e32 v[52:53], 0
	v_mov_b64_e32 v[54:55], 0
	v_mov_b64_e32 v[56:57], 0
	v_mov_b64_e32 v[58:59], 0
	v_mov_b64_e32 v[60:61], 0
	v_mov_b64_e32 v[62:63], 0
	v_mov_b64_e32 v[64:65], 0
	v_mov_b64_e32 v[66:67], 0
	v_mov_b64_e32 v[68:69], 0
	v_mov_b64_e32 v[70:71], 0
	v_mov_b64_e32 v[72:73], 0
	v_mov_b64_e32 v[74:75], 0
	v_mov_b64_e32 v[76:77], 0
	v_mov_b64_e32 v[78:79], 0
	v_mov_b64_e32 v[80:81], 0
	v_mov_b64_e32 v[82:83], 0
	v_mov_b64_e32 v[84:85], 0
	v_mov_b64_e32 v[86:87], 0
	v_mov_b64_e32 v[88:89], 0
	v_mov_b64_e32 v[90:91], 0
	v_mov_b64_e32 v[92:93], 0
	v_mov_b64_e32 v[94:95], 0
	v_mov_b64_e32 v[96:97], 0
	v_mov_b64_e32 v[98:99], 0
	v_mov_b64_e32 v[100:101], 0
	v_mov_b64_e32 v[102:103], 0
	v_mov_b64_e32 v[104:105], 0
	v_mov_b64_e32 v[106:107], 0
	v_mov_b64_e32 v[108:109], 0
	v_mov_b64_e32 v[110:111], 0
	v_mov_b64_e32 v[112:113], 0
	v_mov_b64_e32 v[114:115], 0
	v_mov_b64_e32 v[116:117], 0
	v_mov_b64_e32 v[118:119], 0
	v_mov_b64_e32 v[120:121], 0
	v_mov_b64_e32 v[122:123], 0
	v_mov_b64_e32 v[124:125], 0
	v_mov_b64_e32 v[126:127], 0
	v_mov_b64_e32 v[128:129], 0
	s_barrier
	s_branch .LBB0_103
.LBB0_101:
	v_mov_b32_e32 v2, 0
	s_mov_b32 s30, s34
	s_mov_b32 s31, s35
	s_mov_b32 s48, s66
	s_mov_b32 s50, s64
	s_mov_b32 s44, s62
	s_mov_b64 s[54:55], s[74:75]
	s_mov_b64 s[52:53], s[72:73]
	s_mov_b32 s88, s91
	v_mov_b64_e32 v[2:3], 0
	v_mov_b64_e32 v[4:5], 0
	v_mov_b64_e32 v[6:7], 0
	v_mov_b64_e32 v[8:9], 0
	v_mov_b64_e32 v[10:11], 0
	v_mov_b64_e32 v[12:13], 0
	v_mov_b64_e32 v[14:15], 0
	v_mov_b64_e32 v[16:17], 0
	v_mov_b64_e32 v[18:19], 0
	v_mov_b64_e32 v[20:21], 0
	v_mov_b64_e32 v[22:23], 0
	v_mov_b64_e32 v[24:25], 0
	v_mov_b64_e32 v[26:27], 0
	v_mov_b64_e32 v[28:29], 0
	v_mov_b64_e32 v[30:31], 0
	v_mov_b64_e32 v[32:33], 0
	v_mov_b64_e32 v[34:35], 0
	v_mov_b64_e32 v[36:37], 0
	v_mov_b64_e32 v[38:39], 0
	v_mov_b64_e32 v[40:41], 0
	v_mov_b64_e32 v[42:43], 0
	v_mov_b64_e32 v[44:45], 0
	v_mov_b64_e32 v[46:47], 0
	v_mov_b64_e32 v[48:49], 0
	v_mov_b64_e32 v[50:51], 0
	v_mov_b64_e32 v[52:53], 0
	v_mov_b64_e32 v[54:55], 0
	v_mov_b64_e32 v[56:57], 0
	v_mov_b64_e32 v[58:59], 0
	v_mov_b64_e32 v[60:61], 0
	v_mov_b64_e32 v[62:63], 0
	v_mov_b64_e32 v[64:65], 0
	v_mov_b64_e32 v[66:67], 0
	v_mov_b64_e32 v[68:69], 0
	v_mov_b64_e32 v[70:71], 0
	v_mov_b64_e32 v[72:73], 0
	v_mov_b64_e32 v[74:75], 0
	v_mov_b64_e32 v[76:77], 0
	v_mov_b64_e32 v[78:79], 0
	v_mov_b64_e32 v[80:81], 0
	v_mov_b64_e32 v[82:83], 0
	v_mov_b64_e32 v[84:85], 0
	v_mov_b64_e32 v[86:87], 0
	v_mov_b64_e32 v[88:89], 0
	v_mov_b64_e32 v[90:91], 0
	v_mov_b64_e32 v[92:93], 0
	v_mov_b64_e32 v[94:95], 0
	v_mov_b64_e32 v[96:97], 0
	v_mov_b64_e32 v[98:99], 0
	v_mov_b64_e32 v[100:101], 0
	v_mov_b64_e32 v[102:103], 0
	v_mov_b64_e32 v[104:105], 0
	v_mov_b64_e32 v[106:107], 0
	v_mov_b64_e32 v[108:109], 0
	v_mov_b64_e32 v[110:111], 0
	v_mov_b64_e32 v[112:113], 0
	v_mov_b64_e32 v[114:115], 0
	v_mov_b64_e32 v[116:117], 0
	v_mov_b64_e32 v[118:119], 0
	v_mov_b64_e32 v[120:121], 0
	v_mov_b64_e32 v[122:123], 0
	v_mov_b64_e32 v[124:125], 0
	v_mov_b64_e32 v[126:127], 0
	v_mov_b64_e32 v[128:129], 0

.LBB0_182:
	v_lshrrev_b32_e32 v18, 1, v10
	v_and_b32_e32 v18, 24, v18
	s_add_u32 s72, s8, 0x3a500000
	v_and_b32_e32 v17, 15, v10
	v_lshlrev_b32_e32 v19, 1, v18
	v_lshlrev_b32_e32 v10, 2, v10
	s_addc_u32 s73, s9, 0
	v_lshl_or_b32 v144, s24, 6, v17
	v_lshl_or_b32 v17, v17, 6, v19
	s_lshl_b32 s24, s24, 13
	v_and_b32_e32 v10, 32, v10
	v_bitop3_b32 v19, v17, s24, v10 bitop3:0xde
	s_lshl_b32 s24, s25, 5
	s_and_b32 s27, s24, 0x60
	s_add_i32 m0, s19, 0x18000
	v_lshl_add_u64 v[8:9], v[8:9], 0, s[80:81]
	s_lshl_b32 s24, s27, 7
	s_waitcnt vmcnt(2)
	s_barrier
	global_load_lds_dwordx4 v[8:9], off
	v_lshl_add_u64 v[6:7], v[6:7], 0, s[80:81]
	s_add_i32 m0, s19, 0x1a000
	s_add_i32 s74, s19, 0x8000
	s_add_i32 s75, s19, 0xa000
	v_bitop3_b32 v145, v17, s24, v10 bitop3:0xde
	global_load_lds_dwordx4 v[6:7], off
	v_lshl_add_u64 v[2:3], v[2:3], 0, s[80:81]
	s_mov_b32 m0, s74
	s_add_u32 s24, s48, 0x40080
	global_load_lds_dwordx4 v[2:3], off
	v_lshl_add_u64 v[2:3], v[4:5], 0, s[80:81]
	s_mov_b32 m0, s75
	s_addc_u32 s25, s49, 0
	global_load_lds_dwordx4 v[2:3], off
	s_add_i32 m0, s19, 0x1c000
	v_lshl_add_u64 v[2:3], s[24:25], 0, v[0:1]
	global_load_lds_dwordx4 v[2:3], off
	v_lshl_add_u64 v[2:3], s[24:25], 0, v[134:135]
	s_add_i32 m0, s19, 0x1e000
	s_mov_b64 s[12:13], 0x40080
	global_load_lds_dwordx4 v[2:3], off
	v_lshlrev_b32_e32 v2, 14, v11
	v_and_b32_e32 v2, 0xffff8000, v2
	v_lshl_add_u32 v2, v12, 11, v2
	v_and_b32_e32 v3, 1, v11
	v_lshl_or_b32 v2, v3, 6, v2
	v_lshl_add_u32 v2, v13, 1, v2
	v_mov_b32_e32 v3, v1
	v_lshl_add_u64 v[136:137], v[2:3], 0, s[12:13]
	v_lshlrev_b32_e32 v2, 14, v14
	v_and_b32_e32 v2, 0xffff8000, v2
	v_lshl_add_u32 v2, v15, 11, v2
	v_and_b32_e32 v3, 1, v14
	v_lshl_or_b32 v2, v3, 6, v2
	s_waitcnt vmcnt(6)
	v_lshl_add_u32 v2, v16, 1, v2
	v_mov_b32_e32 v3, v1
	s_cmpk_lt_u32 s26, 0x100
	v_lshl_add_u64 v[138:139], v[2:3], 0, s[12:13]
	v_mov_b32_e32 v2, 0
	s_cselect_b64 s[52:53], -1, 0
	v_or_b32_e32 v150, s27, v18
	s_mov_b32 s86, 0
	v_add_u32_e32 v151, 0, v19
	v_mov_b64_e32 v[2:3], 0
	v_mov_b64_e32 v[4:5], 0
	v_mov_b64_e32 v[6:7], 0
	v_mov_b64_e32 v[8:9], 0
	v_mov_b64_e32 v[10:11], 0
	v_mov_b64_e32 v[12:13], 0
	v_mov_b64_e32 v[14:15], 0
	v_mov_b64_e32 v[16:17], 0
	v_mov_b64_e32 v[18:19], 0
	v_mov_b64_e32 v[20:21], 0
	v_mov_b64_e32 v[22:23], 0
	v_mov_b64_e32 v[24:25], 0
	v_mov_b64_e32 v[26:27], 0
	v_mov_b64_e32 v[28:29], 0
	v_mov_b64_e32 v[30:31], 0
	v_mov_b64_e32 v[32:33], 0
	v_mov_b64_e32 v[34:35], 0
	v_mov_b64_e32 v[36:37], 0
	v_mov_b64_e32 v[38:39], 0
	v_mov_b64_e32 v[40:41], 0
	v_mov_b64_e32 v[42:43], 0
	v_mov_b64_e32 v[44:45], 0
	v_mov_b64_e32 v[46:47], 0
	v_mov_b64_e32 v[48:49], 0
	v_mov_b64_e32 v[50:51], 0
	v_mov_b64_e32 v[52:53], 0
	v_mov_b64_e32 v[54:55], 0
	v_mov_b64_e32 v[56:57], 0
	v_mov_b64_e32 v[58:59], 0
	v_mov_b64_e32 v[60:61], 0
	v_mov_b64_e32 v[62:63], 0
	v_mov_b64_e32 v[64:65], 0
	v_mov_b64_e32 v[66:67], 0
	v_mov_b64_e32 v[68:69], 0
	v_mov_b64_e32 v[70:71], 0
	v_mov_b64_e32 v[72:73], 0
	v_mov_b64_e32 v[74:75], 0
	v_mov_b64_e32 v[76:77], 0
	v_mov_b64_e32 v[78:79], 0
	v_mov_b64_e32 v[80:81], 0
	v_mov_b64_e32 v[82:83], 0
	v_mov_b64_e32 v[84:85], 0
	v_mov_b64_e32 v[86:87], 0
	v_mov_b64_e32 v[88:89], 0
	v_mov_b64_e32 v[90:91], 0
	v_mov_b64_e32 v[92:93], 0
	v_mov_b64_e32 v[94:95], 0
	v_mov_b64_e32 v[96:97], 0
	v_mov_b64_e32 v[98:99], 0
	v_mov_b64_e32 v[100:101], 0
	v_mov_b64_e32 v[102:103], 0
	v_mov_b64_e32 v[104:105], 0
	v_mov_b64_e32 v[106:107], 0
	v_mov_b64_e32 v[108:109], 0
	v_mov_b64_e32 v[110:111], 0
	v_mov_b64_e32 v[112:113], 0
	v_mov_b64_e32 v[114:115], 0
	v_mov_b64_e32 v[116:117], 0
	v_mov_b64_e32 v[118:119], 0
	v_mov_b64_e32 v[120:121], 0
	v_mov_b64_e32 v[122:123], 0
	v_mov_b64_e32 v[124:125], 0
	v_mov_b64_e32 v[126:127], 0
	v_mov_b64_e32 v[128:129], 0
	s_barrier
	s_branch .LBB0_185
.LBB0_183:
	v_mov_b32_e32 v2, 0
	s_mov_b32 s14, s91
	s_mov_b32 s15, s95
	s_mov_b32 s20, s58
	s_mov_b32 s34, s56
	s_mov_b32 s18, s54
	s_mov_b64 s[48:49], s[64:65]
	s_mov_b64 s[46:47], s[62:63]
	s_mov_b32 s86, s88
	v_mov_b64_e32 v[2:3], 0
	v_mov_b64_e32 v[4:5], 0
	v_mov_b64_e32 v[6:7], 0
	v_mov_b64_e32 v[8:9], 0
	v_mov_b64_e32 v[10:11], 0
	v_mov_b64_e32 v[12:13], 0
	v_mov_b64_e32 v[14:15], 0
	v_mov_b64_e32 v[16:17], 0
	v_mov_b64_e32 v[18:19], 0
	v_mov_b64_e32 v[20:21], 0
	v_mov_b64_e32 v[22:23], 0
	v_mov_b64_e32 v[24:25], 0
	v_mov_b64_e32 v[26:27], 0
	v_mov_b64_e32 v[28:29], 0
	v_mov_b64_e32 v[30:31], 0
	v_mov_b64_e32 v[32:33], 0
	v_mov_b64_e32 v[34:35], 0
	v_mov_b64_e32 v[36:37], 0
	v_mov_b64_e32 v[38:39], 0
	v_mov_b64_e32 v[40:41], 0
	v_mov_b64_e32 v[42:43], 0
	v_mov_b64_e32 v[44:45], 0
	v_mov_b64_e32 v[46:47], 0
	v_mov_b64_e32 v[48:49], 0
	v_mov_b64_e32 v[50:51], 0
	v_mov_b64_e32 v[52:53], 0
	v_mov_b64_e32 v[54:55], 0
	v_mov_b64_e32 v[56:57], 0
	v_mov_b64_e32 v[58:59], 0
	v_mov_b64_e32 v[60:61], 0
	v_mov_b64_e32 v[62:63], 0
	v_mov_b64_e32 v[64:65], 0
	v_mov_b64_e32 v[66:67], 0
	v_mov_b64_e32 v[68:69], 0
	v_mov_b64_e32 v[70:71], 0
	v_mov_b64_e32 v[72:73], 0
	v_mov_b64_e32 v[74:75], 0
	v_mov_b64_e32 v[76:77], 0
	v_mov_b64_e32 v[78:79], 0
	v_mov_b64_e32 v[80:81], 0
	v_mov_b64_e32 v[82:83], 0
	v_mov_b64_e32 v[84:85], 0
	v_mov_b64_e32 v[86:87], 0
	v_mov_b64_e32 v[88:89], 0
	v_mov_b64_e32 v[90:91], 0
	v_mov_b64_e32 v[92:93], 0
	v_mov_b64_e32 v[94:95], 0
	v_mov_b64_e32 v[96:97], 0
	v_mov_b64_e32 v[98:99], 0
	v_mov_b64_e32 v[100:101], 0
	v_mov_b64_e32 v[102:103], 0
	v_mov_b64_e32 v[104:105], 0
	v_mov_b64_e32 v[106:107], 0
	v_mov_b64_e32 v[108:109], 0
	v_mov_b64_e32 v[110:111], 0
	v_mov_b64_e32 v[112:113], 0
	v_mov_b64_e32 v[114:115], 0
	v_mov_b64_e32 v[116:117], 0
	v_mov_b64_e32 v[118:119], 0
	v_mov_b64_e32 v[120:121], 0
	v_mov_b64_e32 v[122:123], 0
	v_mov_b64_e32 v[124:125], 0
	v_mov_b64_e32 v[126:127], 0
	v_mov_b64_e32 v[128:129], 0

.LBB0_803:
	s_ashr_i32 s49, s48, 31
	s_lshl_b64 s[14:15], s[48:49], 19
	v_readlane_b32 s12, v254, 47
	v_readlane_b32 s13, v254, 48
	s_add_u32 s52, s12, s14
	s_addc_u32 s53, s13, s15
	s_and_b64 s[14:15], s[44:45], exec
	s_cselect_b32 s3, s53, s27
	s_cselect_b32 s14, s52, s26
	s_ashr_i32 s51, s50, 31
	s_lshl_b64 s[28:29], s[50:51], 19
	v_readlane_b32 s12, v254, 53
	s_add_u32 s54, s12, s28
	v_readlane_b32 s12, v254, 54
	s_addc_u32 s55, s12, s29
	s_and_b64 s[28:29], s[44:45], exec
	s_cselect_b32 s15, s55, s25
	s_cselect_b32 s28, s54, s24
	s_add_u32 s46, s26, 0x40080
	s_addc_u32 s47, s27, 0
	s_add_u32 s29, s24, 0x100
	v_mov_b32_e32 v2, 0
	s_addc_u32 s49, s25, 0
	s_mov_b32 s51, -2
	v_mov_b64_e32 v[2:3], 0
	v_mov_b64_e32 v[4:5], 0
	v_mov_b64_e32 v[6:7], 0
	v_mov_b64_e32 v[8:9], 0
	v_mov_b64_e32 v[10:11], 0
	v_mov_b64_e32 v[12:13], 0
	v_mov_b64_e32 v[14:15], 0
	v_mov_b64_e32 v[16:17], 0
	v_mov_b64_e32 v[18:19], 0
	v_mov_b64_e32 v[20:21], 0
	v_mov_b64_e32 v[22:23], 0
	v_mov_b64_e32 v[24:25], 0
	v_mov_b64_e32 v[34:35], 0
	v_mov_b64_e32 v[36:37], 0
	v_mov_b64_e32 v[38:39], 0
	v_mov_b64_e32 v[40:41], 0
	v_mov_b64_e32 v[50:51], 0
	v_mov_b64_e32 v[52:53], 0
	v_mov_b64_e32 v[54:55], 0
	v_mov_b64_e32 v[56:57], 0
	v_mov_b64_e32 v[58:59], 0
	v_mov_b64_e32 v[60:61], 0
	v_mov_b64_e32 v[62:63], 0
	v_mov_b64_e32 v[64:65], 0
	v_mov_b64_e32 v[66:67], 0
	v_mov_b64_e32 v[68:69], 0
	v_mov_b64_e32 v[70:71], 0
	v_mov_b64_e32 v[72:73], 0
	v_mov_b64_e32 v[74:75], 0
	v_mov_b64_e32 v[76:77], 0
	v_mov_b64_e32 v[78:79], 0
	v_mov_b64_e32 v[80:81], 0
	v_mov_b64_e32 v[82:83], 0
	v_mov_b64_e32 v[84:85], 0
	v_mov_b64_e32 v[86:87], 0
	v_mov_b64_e32 v[88:89], 0
	v_mov_b64_e32 v[90:91], 0
	v_mov_b64_e32 v[92:93], 0
	v_mov_b64_e32 v[94:95], 0
	v_mov_b64_e32 v[96:97], 0
	v_mov_b64_e32 v[98:99], 0
	v_mov_b64_e32 v[100:101], 0
	v_mov_b64_e32 v[102:103], 0
	v_mov_b64_e32 v[104:105], 0
	v_mov_b64_e32 v[106:107], 0
	v_mov_b64_e32 v[108:109], 0
	v_mov_b64_e32 v[110:111], 0
	v_mov_b64_e32 v[112:113], 0
	v_mov_b64_e32 v[114:115], 0
	v_mov_b64_e32 v[116:117], 0
	v_mov_b64_e32 v[118:119], 0
	v_mov_b64_e32 v[120:121], 0
	v_mov_b64_e32 v[122:123], 0
	v_mov_b64_e32 v[124:125], 0
	v_mov_b64_e32 v[126:127], 0
	v_mov_b64_e32 v[128:129], 0
	v_mov_b64_e32 v[130:131], 0
	v_mov_b64_e32 v[132:133], 0
	v_mov_b64_e32 v[134:135], 0
	v_mov_b64_e32 v[136:137], 0
	v_mov_b64_e32 v[138:139], 0
	v_mov_b64_e32 v[140:141], 0
	v_mov_b64_e32 v[142:143], 0
	v_mov_b64_e32 v[144:145], 0
